# speedup vs baseline: 1.0097x; 1.0097x over previous
;     __device__ __forceinline__ void operator()(f32x4 (&acc)[2][2][4][2], const Unit& u, int wr, int wc, int fr, int fq) const {
;     ...
;         const bool fin = u.s == 2;
;         const char* g1 = ga + (u.s == 0 ? 0L : (u.s == 1 ? G1 : G2));
;         const char* g2 = ga + (u.s == 0 ? G1 : G2);
; #pragma unroll
;         for (int ai = 0; ai < 2; ++ai)
; #pragma unroll
;             for (int mp = 0; mp < 2; ++mp) {
;                 u32x4 x1[2][2], x2[2][2];
; #pragma unroll
;                 for (int mi = 0; mi < 2; ++mi) { const int row = row0 + ai * HALF + (2 * mp + mi) * 16; const unsigned goff = ((unsigned)row * (unsigned)ldg + (unsigned)col0) * 2u;
; #pragma unroll
;                     for (int bj = 0; bj < 2; ++bj) { x1[mi][bj] = *(const u32x4*)(g1 + goff + bj * HALF * 2); x2[mi][bj] = x1[mi][bj]; if (!fin) x2[mi][bj] = *(const u32x4*)(g2 + goff + bj * HALF * 2); } }
.LBB0_460:
	s_cmp_eq_u32 s20, 2
	s_cselect_b64 s[6:7], -1, 0
	s_cmp_lg_u32 s20, 2
	v_lshl_or_b32 v192, s22, 8, v171
	s_cselect_b64 s[8:9], -1, 0
	s_cmp_eq_u32 s20, 1
	s_movk_i32 s22, 0x1000
	s_cselect_b32 s20, s22, 0x2000
	s_and_b64 s[34:35], s[10:11], exec
	v_lshl_add_u32 v193, s33, 8, v33
	s_cselect_b32 s20, 0, s20
	s_add_u32 s34, s50, s20
	v_mad_u64_u32 v[194:195], s[36:37], v193, s63, v[192:193]
	s_addc_u32 s35, s51, 0
	v_lshlrev_b32_e32 v130, 1, v194
	global_load_dwordx4 v[154:157], v130, s[34:35]
	s_and_b64 s[10:11], s[10:11], exec
	s_cselect_b32 s10, s22, 0x2000
	s_add_u32 s36, s50, s10
	v_mov_b32_e32 v131, v32
	s_addc_u32 s37, s51, 0
	v_lshl_add_u64 v[166:167], s[36:37], 0, v[130:131]
	v_lshl_add_u64 v[164:165], s[34:35], 0, v[130:131]
	global_load_dwordx4 v[150:153], v[164:165], off offset:256
	v_cndmask_b32_e64 v164, 0, 1, s[8:9]
	s_nop 0
	v_cmp_ne_u32_e64 s[10:11], 1, v164
	v_lshl_add_u32 v164, v194, 1, v213
	global_load_dwordx4 v[142:145], v164, s[34:35]
	v_mov_b32_e32 v165, v32
	v_lshl_add_u64 v[196:197], s[36:37], 0, v[164:165]
	v_lshl_add_u64 v[164:165], s[34:35], 0, v[164:165]
	global_load_dwordx4 v[134:137], v[164:165], off offset:256
	s_and_b64 vcc, exec, s[6:7]
	s_cbranch_vccnz .Lef_fin_0
	global_load_dwordx4 v[158:161], v[166:167], off
	global_load_dwordx4 v[146:149], v[166:167], off offset:256
	global_load_dwordx4 v[138:141], v[196:197], off
	global_load_dwordx4 v[130:133], v[196:197], off offset:256
	s_waitcnt vmcnt(0)
	s_branch .LBB0_468
.Lef_fin_0:
	s_waitcnt vmcnt(0)
	v_mov_b64_e32 v[158:159], v[154:155]
	v_mov_b64_e32 v[160:161], v[156:157]
	v_mov_b64_e32 v[146:147], v[150:151]
	v_mov_b64_e32 v[148:149], v[152:153]
	v_mov_b64_e32 v[138:139], v[142:143]
	v_mov_b64_e32 v[140:141], v[144:145]
	v_mov_b64_e32 v[130:131], v[134:135]
	v_mov_b64_e32 v[132:133], v[136:137]

;     __device__ __forceinline__ void operator()(f32x4 (&acc)[2][2][4][2], const Unit& u, int wr, int wc, int fr, int fq) const {
;     ...
;                 for (int mi = 0; mi < 2; ++mi) { const int row = row0 + ai * HALF + (2 * mp + mi) * 16; const unsigned goff = ((unsigned)row * (unsigned)ldg + (unsigned)col0) * 2u;
; #pragma unroll
;                     for (int bj = 0; bj < 2; ++bj) { x1[mi][bj] = *(const u32x4*)(g1 + goff + bj * HALF * 2); x2[mi][bj] = x1[mi][bj]; if (!fin) x2[mi][bj] = *(const u32x4*)(g2 + goff + bj * HALF * 2); } }
.LBB0_476:
	s_nop 1
	v_lshl_add_u32 v164, v194, 1, v214
	global_load_dwordx4 v[158:161], v164, s[34:35]
	v_mov_b32_e32 v165, v32
	v_lshl_add_u64 v[166:167], s[36:37], 0, v[164:165]
	v_lshl_add_u64 v[164:165], s[34:35], 0, v[164:165]
	global_load_dwordx4 v[150:153], v[164:165], off offset:256
	v_lshl_add_u32 v164, v194, 1, v215
	global_load_dwordx4 v[142:145], v164, s[34:35]
	v_mov_b32_e32 v165, v32
	v_lshl_add_u64 v[196:197], s[36:37], 0, v[164:165]
	v_lshl_add_u64 v[164:165], s[34:35], 0, v[164:165]
	global_load_dwordx4 v[134:137], v[164:165], off offset:256
	s_and_b64 vcc, exec, s[10:11]
	s_cbranch_vccnz .Lef_fin_1
	global_load_dwordx4 v[154:157], v[166:167], off
	global_load_dwordx4 v[146:149], v[166:167], off offset:256
	global_load_dwordx4 v[138:141], v[196:197], off
	global_load_dwordx4 v[130:133], v[196:197], off offset:256
	s_waitcnt vmcnt(0)
	s_branch .LBB0_484
.Lef_fin_1:
	s_waitcnt vmcnt(0)
	v_mov_b64_e32 v[154:155], v[158:159]
	v_mov_b64_e32 v[156:157], v[160:161]
	v_mov_b64_e32 v[146:147], v[150:151]
	v_mov_b64_e32 v[148:149], v[152:153]
	v_mov_b64_e32 v[138:139], v[142:143]
	v_mov_b64_e32 v[140:141], v[144:145]
	v_mov_b64_e32 v[130:131], v[134:135]
	v_mov_b64_e32 v[132:133], v[136:137]

;     __device__ __forceinline__ void operator()(f32x4 (&acc)[2][2][4][2], const Unit& u, int wr, int wc, int fr, int fq) const {
;     ...
;                 for (int mi = 0; mi < 2; ++mi) { const int row = row0 + ai * HALF + (2 * mp + mi) * 16; const unsigned goff = ((unsigned)row * (unsigned)ldg + (unsigned)col0) * 2u;
; #pragma unroll
;                     for (int bj = 0; bj < 2; ++bj) { x1[mi][bj] = *(const u32x4*)(g1 + goff + bj * HALF * 2); x2[mi][bj] = x1[mi][bj]; if (!fin) x2[mi][bj] = *(const u32x4*)(g2 + goff + bj * HALF * 2); } }
.LBB0_492:
	s_nop 1
	v_lshl_add_u32 v164, v194, 1, v216
	global_load_dwordx4 v[158:161], v164, s[34:35]
	v_mov_b32_e32 v165, v32
	v_lshl_add_u64 v[166:167], s[36:37], 0, v[164:165]
	v_lshl_add_u64 v[164:165], s[34:35], 0, v[164:165]
	global_load_dwordx4 v[150:153], v[164:165], off offset:256
	v_lshl_add_u32 v164, v194, 1, v217
	global_load_dwordx4 v[142:145], v164, s[34:35]
	v_mov_b32_e32 v165, v32
	v_lshl_add_u64 v[196:197], s[36:37], 0, v[164:165]
	v_lshl_add_u64 v[164:165], s[34:35], 0, v[164:165]
	global_load_dwordx4 v[134:137], v[164:165], off offset:256
	s_and_b64 vcc, exec, s[10:11]
	s_cbranch_vccnz .Lef_fin_2
	global_load_dwordx4 v[154:157], v[166:167], off
	global_load_dwordx4 v[146:149], v[166:167], off offset:256
	global_load_dwordx4 v[138:141], v[196:197], off
	global_load_dwordx4 v[130:133], v[196:197], off offset:256
	s_waitcnt vmcnt(0)
	s_branch .LBB0_500

;     __device__ __forceinline__ void operator()(f32x4 (&acc)[2][2][4][2], const Unit& u, int wr, int wc, int fr, int fq) const {
;     ...
;                 for (int mi = 0; mi < 2; ++mi) { const int row = row0 + ai * HALF + (2 * mp + mi) * 16; const unsigned goff = ((unsigned)row * (unsigned)ldg + (unsigned)col0) * 2u;
; #pragma unroll
;                     for (int bj = 0; bj < 2; ++bj) { x1[mi][bj] = *(const u32x4*)(g1 + goff + bj * HALF * 2); x2[mi][bj] = x1[mi][bj]; if (!fin) x2[mi][bj] = *(const u32x4*)(g2 + goff + bj * HALF * 2); } }
.LBB0_508:
	s_nop 1
	v_lshl_add_u32 v164, v194, 1, v218
	global_load_dwordx4 v[158:161], v164, s[34:35]
	v_mov_b32_e32 v165, v32
	v_lshl_add_u64 v[166:167], s[36:37], 0, v[164:165]
	v_lshl_add_u64 v[164:165], s[34:35], 0, v[164:165]
	global_load_dwordx4 v[150:153], v[164:165], off offset:256
	v_lshl_add_u32 v164, v194, 1, v219
	global_load_dwordx4 v[142:145], v164, s[34:35]
	v_mov_b32_e32 v165, v32
	v_lshl_add_u64 v[194:195], s[36:37], 0, v[164:165]
	v_lshl_add_u64 v[164:165], s[34:35], 0, v[164:165]
	global_load_dwordx4 v[134:137], v[164:165], off offset:256
	s_and_b64 vcc, exec, s[10:11]
	s_cbranch_vccnz .Lef_fin_3
	global_load_dwordx4 v[154:157], v[166:167], off
	global_load_dwordx4 v[146:149], v[166:167], off offset:256
	global_load_dwordx4 v[138:141], v[194:195], off
	global_load_dwordx4 v[130:133], v[194:195], off offset:256
	s_waitcnt vmcnt(0)
	s_branch .LBB0_516
